# P2 queue: next item claimed early only while the current index is in the first (long) half of the attention items; tail items still claimed synchronously
# speedup vs baseline: 1.0158x; 1.0027x over previous
; DI void attn_item(const Params& p, unsigned char* lds, int b, int hd, int qb, float lam) {
;     ...
;     const int qs = qb * 128 + rt * 32 + l31;
;     const size_t grow = (size_t)b * 4096 + qs;
;     bf16x8 qf[4];
; #pragma unroll
;     for (int ks = 0; ks < 4; ++ks) qf[ks] = *(const bf16x8*)(aq + grow * 1024 + hd * 128 + sub * 64 + ks * 16 + 8 * h);
;     f32x16 O[4];
; #pragma unroll
;     for (int d = 0; d < 4; ++d)
; #pragma unroll
;         for (int i = 0; i < 16; ++i) O[d][i] = 0.f;
;     float m = 0.f, l = 0.f;
;     const int T = 2 * qb + 3;
;     u32x4 k0r[2], v0r[2];
;     const int krow_ = tid >> 4, kc_ = tid & 15, vdv_ = tid >> 3, vc_ = tid & 7;
;     const bf16_t* kp = ak + ((size_t)b * 4096 + krow_) * 1024 + hd * 128 + kc_ * 8;
;     const bf16_t* vp_ = avT + ((size_t)(b * 8 + hd) * 128 + vdv_) * 4096 + vc_ * 8;
;     ...
;     {
;         const bf16_t* km_ = akm + (size_t)krow_ * 1024 + hd * 128 + kc_ * 8;
;         k0r[0] = *(const u32x4*)km_; k0r[1] = *(const u32x4*)(km_ + 32 * 1024);
;         const bf16_t* vm_ = avTm + (size_t)(hd * 128 + vdv_) * 64 + vc_ * 8;
;         v0r[0] = *(const u32x4*)vm_; v0r[1] = *(const u32x4*)(vm_ + 64 * 64);
;     }
;     u32x4 k1r[2], v1r[2];
;     A_LOAD_REAL(k1r, v1r);
; #pragma unroll
;     for (int ks = 0; ks < 4; ++ks) asm volatile("" : "+v"(qf[ks]));
;     A_STORE(k0r, v0r, 0);
; DI void phase2(const Params& p, unsigned char* lds) {
;     ...
;         const unsigned item = (unsigned)__builtin_amdgcn_readfirstlane((int)sItem[0]);
;         __syncthreads();
;         if (item == 0xffffffffu) break;
;         const unsigned x = item >> 16, idx = item & 0xffffu;
;         if (idx < N_GLA) { const unsigned gi = x * N_GLA + idx; gla_item<GLA_DL>(p, lds, gi / (4 * NSL), (gi / NSL) & 3, gi % NSL); }
;         else { const unsigned a = idx - N_GLA, pair = 4 * x + ((a >> 2) & 3); attn_item(p, lds, pair & 3, pair >> 2, 31 - (int)(((a >> 4) << 2) + (a & 3)), lam); }
.LBB0_1809:
	s_or_b64 exec, exec, s[4:5]
	s_add_i32 s0, 0, 0x25000
	s_cmp_lg_u32 s0, -1
	s_cselect_b32 s0, s0, 0
	s_cselect_b32 s4, s57, 0
	s_waitcnt vmcnt(0)
	v_mov_b32_e32 v2, s0
	v_mov_b32_e32 v3, s4
	s_waitcnt lgkmcnt(0)
	s_barrier
	ds_read_b32 v1, v2
	s_waitcnt vmcnt(0) lgkmcnt(0)
	s_barrier
	v_readfirstlane_b32 s8, v1
	s_cmp_eq_u32 s8, -1
	s_cbranch_scc1 .LBB0_1823
	s_lshr_b32 s9, s8, 16
	s_and_b32 s0, s8, 0xffff
	s_cmp_gt_u32 s0, 7
	s_mov_b64 s[4:5], -1
	s_cbranch_scc0 .LBB0_1831
	v_mov_b32_e32 v238, -1
	s_cmp_gt_u32 s0, 71
	s_cbranch_scc1 .Lq_noclaim
	s_and_saveexec_b64 s[4:5], s[40:41]
	v_lshlrev_b32_e64 v238, 2, s9
	s_nop 0
	global_atomic_add v238, v238, v187, s[58:59] sc0
	s_mov_b64 exec, s[4:5]
.Lq_noclaim:
	s_add_i32 s4, s0, -8
	s_lshr_b32 s0, s4, 2
	s_and_b32 s0, s0, 0x3ffffffc
	s_and_b32 s5, s8, 3
	s_or_b32 s0, s0, s5
	v_mov_b32_e32 v132, v186
	s_sub_i32 s0, 31, s0
	s_lshl_b32 s6, s0, 7
	v_lshrrev_b32_e32 v1, 1, v132
	v_and_b32_e32 v146, 31, v132
	v_and_b32_e32 v148, 0x60, v1
	s_bfe_u32 s11, s4, 0x20002
	v_or3_b32 v138, v148, s6, v146
	s_lshl_b32 s54, s11, 12
	v_ashrrev_i32_e32 v139, 31, v138
	v_lshl_add_u64 v[2:3], v[138:139], 0, s[54:55]
	v_ashrrev_i32_e32 v147, 8, v132
	v_lshlrev_b64 v[136:137], 11, v[2:3]
	v_lshl_add_u64 v[2:3], s[68:69], 0, v[136:137]
	s_lshl_b32 s6, s9, 8
	s_mov_b32 s7, s55
	v_lshlrev_b32_e32 v4, 6, v147
	v_lshl_add_u64 v[2:3], v[2:3], 0, s[6:7]
	v_ashrrev_i32_e32 v5, 31, v4
	v_lshl_add_u64 v[2:3], v[4:5], 1, v[2:3]
	v_ashrrev_i32_e32 v4, 4, v132
	v_ashrrev_i32_e32 v5, 31, v4
	v_lshlrev_b64 v[12:13], 11, v[4:5]
	v_bfe_u32 v149, v132, 5, 1
	v_lshlrev_b32_e32 v1, 4, v132
	v_lshl_add_u64 v[12:13], s[64:65], 0, v[12:13]
	v_lshlrev_b32_e32 v98, 4, v149
	v_and_b32_e32 v140, 0xf0, v1
	v_mov_b32_e32 v141, v99
	v_lshl_add_u64 v[12:13], v[12:13], 0, s[6:7]
	v_lshl_add_u64 v[2:3], v[2:3], 0, v[98:99]
	v_lshl_add_u64 v[12:13], v[12:13], 0, v[140:141]
	global_load_dwordx4 v[100:103], v[2:3], off
	global_load_dwordx4 v[104:107], v[2:3], off offset:32
	global_load_dwordx4 v[108:111], v[2:3], off offset:64
	global_load_dwordx4 v[112:115], v[2:3], off offset:96
	global_load_dwordx4 v[116:119], v[12:13], off
	v_add_co_u32_e32 v2, vcc, s43, v12
	s_lshl_b32 s10, s9, 7
	v_ashrrev_i32_e32 v6, 3, v132
	v_addc_co_u32_e32 v3, vcc, 0, v13, vcc
	global_load_dwordx4 v[120:123], v[2:3], off
	v_add_u32_e32 v2, s10, v6
	v_ashrrev_i32_e32 v3, 31, v2
	v_lshlrev_b64 v[2:3], 7, v[2:3]
	v_and_b32_e32 v10, 0x70, v1
	v_mov_b32_e32 v11, v99
	v_lshl_add_u64 v[2:3], s[62:63], 0, v[2:3]
	v_lshl_add_u64 v[2:3], v[2:3], 0, v[10:11]
	global_load_dwordx4 v[124:127], v[2:3], off
	v_lshl_add_u64 v[8:9], v[4:5], 0, s[54:55]
	v_lshlrev_b64 v[8:9], 11, v[8:9]
	v_add_co_u32_e32 v2, vcc, s56, v2
	v_lshl_add_u64 v[8:9], s[44:45], 0, v[8:9]
	s_lshl_b32 s11, s11, 10
	v_addc_co_u32_e32 v3, vcc, 0, v3, vcc
	v_lshl_add_u64 v[8:9], v[8:9], 0, s[6:7]
	s_add_i32 s54, s11, s10
	v_ashrrev_i32_e32 v7, 31, v6
	global_load_dwordx4 v[128:131], v[2:3], off
	v_lshl_add_u64 v[82:83], v[8:9], 0, v[140:141]
	v_lshl_add_u64 v[8:9], v[6:7], 0, s[54:55]
	v_lshlrev_b64 v[8:9], 13, v[8:9]
	v_lshl_add_u64 v[8:9], s[60:61], 0, v[8:9]
	v_add_co_u32_e32 v2, vcc, s43, v82
	v_lshl_add_u64 v[84:85], v[8:9], 0, v[10:11]
	s_nop 0
	v_addc_co_u32_e32 v3, vcc, 0, v83, vcc
	v_add_co_u32_e32 v8, vcc, s74, v84
	global_load_dwordx4 v[74:77], v[82:83], off
	global_load_dwordx4 v[70:73], v[84:85], off
	v_addc_co_u32_e32 v9, vcc, 0, v85, vcc
	global_load_dwordx4 v[78:81], v[2:3], off
	global_load_dwordx4 v[66:69], v[8:9], off
	v_lshlrev_b32_e32 v2, 3, v132
	v_mul_lo_u32 v139, v4, s75
	v_add_u32_e32 v4, 0x200, v132
	v_and_b32_e32 v150, 0x60, v1
	v_and_b32_e32 v151, 8, v2
	v_lshrrev_b32_e32 v5, 4, v4
	v_add3_u32 v1, 0, v150, v151
	v_mul_lo_u32 v152, v6, s52
	v_add_u32_e32 v3, 0, v140
	v_mul_lo_u32 v141, v5, s75
	v_add_u32_e32 v97, v1, v152
	v_add_u32_e32 v87, v3, v139
	v_add_u32_e32 v96, v3, v141
	v_add_u32_e32 v2, 0x4000, v97
	s_waitcnt vmcnt(11)
	s_waitcnt vmcnt(10)
	s_waitcnt vmcnt(9)
	s_waitcnt vmcnt(8)
	s_waitcnt vmcnt(7)
	ds_write_b128 v87, v[116:119]
	v_mad_u32_u24 v42, v146, s75, 0
	v_lshl_or_b32 v154, v147, 7, v98
	s_waitcnt vmcnt(6)
	ds_write_b128 v96, v[120:123]
	s_waitcnt vmcnt(5)
	ds_write2_b64 v2, v[124:125], v[126:127] offset0:128 offset1:130
	v_lshrrev_b32_e32 v2, 3, v4
	v_mul_lo_u32 v153, v2, s52
	v_add_u32_e32 v155, v1, v153
	v_add_u32_e32 v1, 0x4000, v155
	s_waitcnt vmcnt(4)
	ds_write2_b64 v1, v[128:129], v[130:131] offset0:128 offset1:130
	v_add_u32_e32 v1, v42, v154
	s_waitcnt lgkmcnt(0)
	s_barrier
; DI void attn_s(const unsigned char* sK, int tt, int qb, int qs, int sub, int l31, int h,
;                const bf16x8 (&qf)[4], f32x16 (&O)[4], float& m, float& l, bf16x8 (&pb)[4]) {
;     ...
;         for (int i = 0; i < 16; ++i) st[k2][i] = -m;
;     {
;         const unsigned char* kb = sK + l31 * A_KROWB + (sub * 64 + 8 * h) * 2;
;         bf16x8 ka[4], kc[4];
; #pragma unroll
;         for (int i = 0; i < 4; ++i) ka[i] = *(const bf16x8*)(kb + (i & 1) * 32 * A_KROWB + (i >> 1) * 32);
;         __builtin_amdgcn_sched_barrier(0);
; #pragma unroll
;         for (int i = 0; i < 4; ++i) kc[i] = *(const bf16x8*)(kb + (i & 1) * 32 * A_KROWB + (2 + (i >> 1)) * 32);
;         __builtin_amdgcn_sched_barrier(0);
; #pragma unroll
;         for (int i = 0; i < 4; ++i) st[i & 1] = MFMA32(ka[i], qf[i >> 1], st[i & 1]);
;         __builtin_amdgcn_sched_barrier(0);
; #pragma unroll
;         for (int i = 0; i < 4; ++i) st[i & 1] = MFMA32(kc[i], qf[2 + (i >> 1)], st[i & 1]);
;     }
;     if (tt == 0) {
; #pragma unroll
;         for (int i = 0; i < 16; ++i) { st[0][i] = -INFINITY; if (i < 8) st[1][i] = -INFINITY; }
;     } else if (tt >= 2 * qb + 1) {
;         const int kbase = (tt - 1) * 64 + 4 * h;
; #pragma unroll
;         for (int k2 = 0; k2 < 2; ++k2)
; #pragma unroll
;             for (int i = 0; i < 16; ++i) {
;                 const int key = kbase + k2 * 32 + (i & 3) + 8 * (i >> 2);
;                 if (key > qs) st[k2][i] = -INFINITY;
;             }
;     }
;     float mx;
;     {
;         float t[11];
; #pragma unroll
;         for (int i = 0; i < 5; ++i) t[i] = max3f(st[0][3 * i], st[0][3 * i + 1], st[0][3 * i + 2]);
; #pragma unroll
;         for (int i = 0; i < 5; ++i) t[5 + i] = max3f(st[1][3 * i], st[1][3 * i + 1], st[1][3 * i + 2]);
;         t[10] = fmaxf(st[0][15], st[1][15]);
;         const float u0 = max3f(t[0], t[1], t[2]), u1 = max3f(t[3], t[4], t[5]), u2 = max3f(t[6], t[7], t[8]);
;         mx = max3f(max3f(u0, u1, u2), t[9], t[10]);
;     }
;     mx = xor32_max(mx);
;     if (tt == 0 || __builtin_amdgcn_ballot_w64(mx > 8.0f) != 0ull) {
;         const float delta = tt == 0 ? mx : fmaxf(mx, 0.f);
;         const float alpha = __builtin_amdgcn_exp2f(-delta);
;         m += delta;
;         l *= alpha;
; #pragma unroll
;         for (int d = 0; d < 4; ++d) O[d] = O[d] * alpha;
; #pragma unroll
	ds_read_b128 v[26:29], v1 offset:8704
	ds_read_b128 v[30:33], v1 offset:8736
	ds_read_b128 v[34:37], v1 offset:8768
	ds_read_b128 v[38:41], v1 offset:8800
	v_mov_b32_e32 v10, v0
	v_mov_b32_e32 v11, v0
	v_mov_b32_e32 v12, v0
	v_mov_b32_e32 v13, v0
	v_mov_b32_e32 v14, v0
	v_mov_b32_e32 v15, v0
	v_mov_b32_e32 v1, v0
	v_mov_b32_e32 v2, v0
	v_mov_b32_e32 v3, v0
	v_mov_b32_e32 v4, v0
	v_mov_b32_e32 v5, v0
	v_mov_b32_e32 v6, v0
	v_mov_b32_e32 v7, v0
	v_mov_b32_e32 v8, v0
	v_mov_b32_e32 v9, v0
	v_mov_b64_e32 v[24:25], v[14:15]
	v_mov_b64_e32 v[22:23], v[12:13]
	v_mov_b64_e32 v[20:21], v[10:11]
	v_mov_b64_e32 v[18:19], v[8:9]
	v_mov_b64_e32 v[16:17], v[6:7]
	v_mov_b64_e32 v[14:15], v[4:5]
	v_mov_b64_e32 v[12:13], v[2:3]
	v_mov_b64_e32 v[10:11], v[0:1]
	s_waitcnt lgkmcnt(3)
	s_nop 0
	v_mfma_f32_32x32x16_bf16 v[10:25], v[26:29], v[100:103], v[10:25]
	s_waitcnt lgkmcnt(2)
	v_mfma_f32_32x32x16_bf16 v[10:25], v[30:33], v[104:107], v[10:25]
	s_waitcnt lgkmcnt(1)
	v_mfma_f32_32x32x16_bf16 v[10:25], v[34:37], v[108:111], v[10:25]
	v_max3_f32 v1, v188, v188, v188
	s_nop 0
	v_max3_f32 v2, v1, v1, v1
	s_waitcnt lgkmcnt(0)
	v_mfma_f32_32x32x16_bf16 v[10:25], v[38:41], v[112:115], v[10:25]
	v_max3_f32 v3, v188, v188, v18
	v_max3_f32 v4, v19, v20, v21
	v_max3_f32 v5, v22, v23, v24
	s_nop 0
	v_max3_f32 v1, v1, v3, v4
	s_nop 10
	v_max_f32_e32 v6, v25, v25
	v_max3_f32 v1, v2, v2, v1
	v_max_f32_e32 v6, 0xff800000, v6
	v_max3_f32 v1, v1, v5, v6
	s_nop 0
	v_mov_b32_e32 v2, v1
	s_nop 1
	v_permlane32_swap_b32_e32 v1, v2
	v_max_f32_e32 v2, v2, v2
	v_max_f32_e32 v1, v1, v1
	v_max_f32_e32 v86, v1, v2
	v_sub_f32_e32 v1, 0xff800000, v86
	v_sub_f32_e32 v19, v19, v86
	v_sub_f32_e32 v26, v18, v86
	v_sub_f32_e32 v21, v21, v86
	v_sub_f32_e32 v20, v20, v86
	v_exp_f32_e32 v18, v1
	v_exp_f32_e32 v26, v26
	v_exp_f32_e32 v27, v19
	v_sub_f32_e32 v23, v23, v86
	v_sub_f32_e32 v22, v22, v86
	v_exp_f32_e32 v28, v20
	v_exp_f32_e32 v29, v21
	v_sub_f32_e32 v25, v25, v86
	v_sub_f32_e32 v24, v24, v86
	v_exp_f32_e32 v30, v22
	v_exp_f32_e32 v31, v23
	v_exp_f32_e32 v32, v24
	v_exp_f32_e32 v33, v25
	v_pk_add_f32 v[34:35], v[18:19], v[26:27] op_sel_hi:[0,1]
	v_add_f32_e32 v36, v18, v18
	v_pk_add_f32 v[24:25], v[18:19], v[28:29] op_sel_hi:[0,1]
	v_mov_b32_e32 v37, v34
	v_mov_b32_e32 v34, v36
	v_pk_add_f32 v[22:23], v[18:19], v[30:31] op_sel_hi:[0,1]
	v_pk_add_f32 v[34:35], v[36:37], v[34:35]
	v_mov_b32_e32 v37, v24
	v_mov_b32_e32 v24, v36
	v_pk_add_f32 v[20:21], v[18:19], v[32:33] op_sel_hi:[0,1]
	v_pk_add_f32 v[24:25], v[36:37], v[24:25]
	v_mov_b32_e32 v37, v22
	v_mov_b32_e32 v22, v36
	v_pk_add_f32 v[22:23], v[36:37], v[22:23]
	v_mov_b32_e32 v37, v20
	v_mov_b32_e32 v20, v36
	v_pk_add_f32 v[20:21], v[36:37], v[20:21]
	v_cvt_pk_bf16_f32 v88, v18, v18
	v_lshlrev_b32_e32 v18, 7, v146
	v_pk_add_f32 v[24:25], v[34:35], v[24:25]
	v_pk_add_f32 v[20:21], v[22:23], v[20:21]
	v_sub_u32_e32 v18, v42, v18
	v_pk_add_f32 v[20:21], v[24:25], v[20:21]
	v_add_u32_e32 v185, v18, v98
	v_add_f32_e32 v1, v20, v21
	ds_read_b128 v[160:163], v185 offset:17504
	ds_read_b128 v[164:167], v185 offset:22112
	ds_read_b128 v[168:171], v185 offset:26720
	ds_read_b128 v[172:175], v185 offset:31328
	v_exp_f32_e64 v184, -v86
	v_mov_b32_e32 v89, v88
	v_mov_b32_e32 v90, v88
	v_mov_b32_e32 v91, v88
	v_mul_f32_e32 v2, 0, v184
	v_mov_b32_e32 v3, v2
	v_mov_b32_e32 v4, v2
	v_mov_b32_e32 v5, v2
	v_mov_b32_e32 v6, v2
	v_mov_b32_e32 v7, v2
	v_mov_b32_e32 v8, v2
	v_mov_b32_e32 v9, v2
	v_mov_b32_e32 v10, v2
	v_mov_b32_e32 v11, v2
	v_mov_b32_e32 v12, v2
	v_mov_b32_e32 v13, v2
	v_mov_b32_e32 v14, v2
	v_mov_b32_e32 v15, v2
	v_mov_b32_e32 v16, v2
	v_mov_b32_e32 v17, v2
	v_cvt_pk_bf16_f32 v156, v26, v27
	v_cvt_pk_bf16_f32 v157, v28, v29
	v_cvt_pk_bf16_f32 v158, v30, v31
	v_cvt_pk_bf16_f32 v159, v32, v33
	s_waitcnt lgkmcnt(3)
	v_mfma_f32_32x32x16_bf16 v[50:65], v[160:163], v[156:159], v[2:17]
	s_waitcnt vmcnt(3)
	ds_write_b128 v87, v[74:77] offset:35840
	s_waitcnt vmcnt(1)
	ds_write_b128 v96, v[78:81] offset:35840
	v_add_u32_e32 v74, 0xd000, v97
	ds_write2_b64 v74, v[70:71], v[72:73] offset1:2
	v_add_u32_e32 v70, 0xd000, v155
	v_fmac_f32_e32 v1, 0, v184
	s_cmpk_gt_u32 s4, 0x7f
	s_waitcnt vmcnt(0)
	ds_write2_b64 v70, v[66:67], v[68:69] offset1:2
	v_readfirstlane_b32 s99, v238
	s_nop 3
	v_writelane_b32 v236, s99, 63
	s_waitcnt lgkmcnt(6)
	v_mfma_f32_32x32x16_bf16 v[34:49], v[164:167], v[156:159], v[2:17]
	s_waitcnt lgkmcnt(0)
	s_barrier
	v_mfma_f32_32x32x16_bf16 v[18:33], v[168:171], v[156:159], v[2:17]
	v_mfma_f32_32x32x16_bf16 v[2:17], v[172:175], v[156:159], v[2:17]
	s_cbranch_scc1 .LBB0_1824
	s_lshr_b32 s4, s4, 1
	s_lshl_b32 s5, s5, 1
	s_and_b32 s4, s4, 0x7ffffff8
	s_lshl_b32 s0, s0, 1
	s_or_b32 s4, s5, s4
	v_mul_u32_u24_e32 v155, 0x110, v146
	v_mul_u32_u24_e32 v156, 0x90, v146
	s_mov_b32 s13, 1
	s_add_i32 s6, s0, 3
	v_lshl_add_u64 v[142:143], v[84:85], 0, s[88:89]
	v_lshl_add_u64 v[142:143], v[142:143], 0, s[88:89]
	v_add_f32_e32 v157, 0, v86
	v_lshl_add_u64 v[144:145], v[82:83], 0, s[90:91]
	v_lshl_add_u64 v[144:145], v[144:145], 0, s[90:91]
	s_mov_b32 s7, 2
	v_lshl_or_b32 v158, v149, 2, 59
	s_sub_i32 s11, 0, s4
	s_movk_i32 s12, 0xffc0
	v_xor_b32_e32 v240, 0x80000000, v157
	v_mov_b32_e32 v241, v240
	v_mov_b32_e32 v242, v240
	v_mov_b32_e32 v243, v240
	v_mov_b32_e32 v244, v240
	v_mov_b32_e32 v245, v240
	v_mov_b32_e32 v246, v240
	v_mov_b32_e32 v247, v240
	v_mov_b32_e32 v248, v240
	v_mov_b32_e32 v249, v240
	v_mov_b32_e32 v250, v240
	v_mov_b32_e32 v251, v240
	v_mov_b32_e32 v252, v240
	v_mov_b32_e32 v253, v240
	v_mov_b32_e32 v254, v240
	v_mov_b32_e32 v255, v240
	v_readfirstlane_b32 s99, v147
	s_cmp_eq_u32 s99, 1
	s_cbranch_scc0 .Lpipe_nooffs
	s_barrier
